# attention main-loop S section restructured: all exp/rowsum/cvt VALU first (P fragments parked in v212-243), then 16 PV MFMAs back-to-back with 8-deep V fragment prefetch
# baseline (speedup 1.0000x reference)
.LBB0_668:
	s_waitcnt lgkmcnt(0)
	s_barrier
	v_add3_u32 v252, s1, v142, v162
	v_add_u32_e32 v252, 0x6800, v252
	v_add_u32_e32 v253, 0x2000, v252
	v_exp_f32_e32 v80, v80
	v_exp_f32_e32 v81, v81
	v_exp_f32_e32 v82, v82
	v_exp_f32_e32 v83, v83
	v_exp_f32_e32 v84, v84
	v_exp_f32_e32 v85, v85
	v_exp_f32_e32 v86, v86
	v_exp_f32_e32 v87, v87
	v_lshl_add_u64 v[150:151], v[150:151], 0, s[14:15]
	v_lshl_add_u64 v[152:153], v[152:153], 0, s[14:15]
	v_lshl_add_u64 v[154:155], v[154:155], 0, s[12:13]
	v_lshl_add_u64 v[156:157], v[156:157], 0, s[12:13]
	v_lshl_add_u64 v[158:159], v[158:159], 0, s[12:13]
	v_exp_f32_e32 v88, v88
	v_exp_f32_e32 v89, v89
	v_exp_f32_e32 v90, v90
	v_exp_f32_e32 v91, v91
	v_exp_f32_e32 v92, v92
	v_exp_f32_e32 v93, v93
	v_exp_f32_e32 v94, v94
	v_exp_f32_e32 v95, v95
	v_add_f32_e32 v254, 0, v80
	v_add_f32_e32 v254, v81, v254
	v_add_f32_e32 v254, v82, v254
	v_add_f32_e32 v254, v83, v254
	v_add_f32_e32 v254, v84, v254
	v_add_f32_e32 v254, v85, v254
	v_add_f32_e32 v254, v86, v254
	v_add_f32_e32 v254, v87, v254
	v_cvt_pk_bf16_f32 v212, v80, v81
	v_cvt_pk_bf16_f32 v213, v82, v83
	v_cvt_pk_bf16_f32 v214, v84, v85
	v_cvt_pk_bf16_f32 v215, v86, v87
	v_exp_f32_e32 v64, v64
	v_exp_f32_e32 v65, v65
	v_exp_f32_e32 v66, v66
	v_exp_f32_e32 v67, v67
	v_exp_f32_e32 v68, v68
	v_exp_f32_e32 v69, v69
	v_exp_f32_e32 v70, v70
	v_exp_f32_e32 v71, v71
	v_add_f32_e32 v254, v88, v254
	v_add_f32_e32 v254, v89, v254
	v_add_f32_e32 v254, v90, v254
	v_add_f32_e32 v254, v91, v254
	v_add_f32_e32 v254, v92, v254
	v_add_f32_e32 v254, v93, v254
	v_add_f32_e32 v254, v94, v254
	v_add_f32_e32 v254, v95, v254
	v_cvt_pk_bf16_f32 v216, v88, v89
	v_cvt_pk_bf16_f32 v217, v90, v91
	v_cvt_pk_bf16_f32 v218, v92, v93
	v_cvt_pk_bf16_f32 v219, v94, v95
	v_exp_f32_e32 v72, v72
	v_exp_f32_e32 v73, v73
	v_exp_f32_e32 v74, v74
	v_exp_f32_e32 v75, v75
	v_exp_f32_e32 v76, v76
	v_exp_f32_e32 v77, v77
	v_exp_f32_e32 v78, v78
	v_exp_f32_e32 v79, v79
	v_add_f32_e32 v254, v64, v254
	v_add_f32_e32 v254, v65, v254
	v_add_f32_e32 v254, v66, v254
	v_add_f32_e32 v254, v67, v254
	v_add_f32_e32 v254, v68, v254
	v_add_f32_e32 v254, v69, v254
	v_add_f32_e32 v254, v70, v254
	v_add_f32_e32 v254, v71, v254
	v_cvt_pk_bf16_f32 v220, v64, v65
	v_cvt_pk_bf16_f32 v221, v66, v67
	v_cvt_pk_bf16_f32 v222, v68, v69
	v_cvt_pk_bf16_f32 v223, v70, v71
	v_exp_f32_e32 v48, v48
	v_exp_f32_e32 v49, v49
	v_exp_f32_e32 v50, v50
	v_exp_f32_e32 v51, v51
	v_exp_f32_e32 v52, v52
	v_exp_f32_e32 v53, v53
	v_exp_f32_e32 v54, v54
	v_exp_f32_e32 v55, v55
	v_add_f32_e32 v254, v72, v254
	v_add_f32_e32 v254, v73, v254
	v_add_f32_e32 v254, v74, v254
	v_add_f32_e32 v254, v75, v254
	v_add_f32_e32 v254, v76, v254
	v_add_f32_e32 v254, v77, v254
	v_add_f32_e32 v254, v78, v254
	v_add_f32_e32 v254, v79, v254
	v_cvt_pk_bf16_f32 v224, v72, v73
	v_cvt_pk_bf16_f32 v225, v74, v75
	v_cvt_pk_bf16_f32 v226, v76, v77
	v_cvt_pk_bf16_f32 v227, v78, v79
	v_exp_f32_e32 v56, v56
	v_exp_f32_e32 v57, v57
	v_exp_f32_e32 v58, v58
	v_exp_f32_e32 v59, v59
	v_exp_f32_e32 v60, v60
	v_exp_f32_e32 v61, v61
	v_exp_f32_e32 v62, v62
	v_exp_f32_e32 v63, v63
	v_add_f32_e32 v254, v48, v254
	v_add_f32_e32 v254, v49, v254
	v_add_f32_e32 v254, v50, v254
	v_add_f32_e32 v254, v51, v254
	v_add_f32_e32 v254, v52, v254
	v_add_f32_e32 v254, v53, v254
	v_add_f32_e32 v254, v54, v254
	v_add_f32_e32 v254, v55, v254
	v_cvt_pk_bf16_f32 v228, v48, v49
	v_cvt_pk_bf16_f32 v229, v50, v51
	v_cvt_pk_bf16_f32 v230, v52, v53
	v_cvt_pk_bf16_f32 v231, v54, v55
	v_exp_f32_e32 v32, v32
	v_exp_f32_e32 v33, v33
	v_exp_f32_e32 v34, v34
	v_exp_f32_e32 v35, v35
	v_exp_f32_e32 v36, v36
	v_exp_f32_e32 v37, v37
	v_exp_f32_e32 v38, v38
	v_exp_f32_e32 v39, v39
	v_add_f32_e32 v254, v56, v254
	v_add_f32_e32 v254, v57, v254
	v_add_f32_e32 v254, v58, v254
	v_add_f32_e32 v254, v59, v254
	v_add_f32_e32 v254, v60, v254
	v_add_f32_e32 v254, v61, v254
	v_add_f32_e32 v254, v62, v254
	v_add_f32_e32 v254, v63, v254
	v_cvt_pk_bf16_f32 v232, v56, v57
	v_cvt_pk_bf16_f32 v233, v58, v59
	v_cvt_pk_bf16_f32 v234, v60, v61
	v_cvt_pk_bf16_f32 v235, v62, v63
	v_exp_f32_e32 v40, v40
	v_exp_f32_e32 v41, v41
	v_exp_f32_e32 v42, v42
	v_exp_f32_e32 v43, v43
	v_exp_f32_e32 v44, v44
	v_exp_f32_e32 v45, v45
	v_exp_f32_e32 v46, v46
	v_exp_f32_e32 v47, v47
	v_add_f32_e32 v254, v32, v254
	v_add_f32_e32 v254, v33, v254
	v_add_f32_e32 v254, v34, v254
	v_add_f32_e32 v254, v35, v254
	v_add_f32_e32 v254, v36, v254
	v_add_f32_e32 v254, v37, v254
	v_add_f32_e32 v254, v38, v254
	v_add_f32_e32 v254, v39, v254
	v_cvt_pk_bf16_f32 v236, v32, v33
	v_cvt_pk_bf16_f32 v237, v34, v35
	v_cvt_pk_bf16_f32 v238, v36, v37
	v_cvt_pk_bf16_f32 v239, v38, v39
	s_nop 0
	v_add_f32_e32 v254, v40, v254
	v_add_f32_e32 v254, v41, v254
	v_add_f32_e32 v254, v42, v254
	v_add_f32_e32 v254, v43, v254
	v_add_f32_e32 v254, v44, v254
	v_add_f32_e32 v254, v45, v254
	v_add_f32_e32 v254, v46, v254
	v_add_f32_e32 v254, v47, v254
	v_cvt_pk_bf16_f32 v240, v40, v41
	v_cvt_pk_bf16_f32 v241, v42, v43
	v_cvt_pk_bf16_f32 v242, v44, v45
	v_cvt_pk_bf16_f32 v243, v46, v47
	v_add_f32_e32 v149, v149, v254
	ds_read2_b64 v[32:35], v252 offset1:2
	ds_read2_b64 v[36:39], v253 offset0:32 offset1:34
	ds_read2_b64 v[40:43], v252 offset0:4 offset1:6
	ds_read2_b64 v[44:47], v253 offset0:36 offset1:38
	ds_read2_b64 v[48:51], v252 offset0:8 offset1:10
	ds_read2_b64 v[52:55], v253 offset0:40 offset1:42
	ds_read2_b64 v[56:59], v252 offset0:12 offset1:14
	ds_read2_b64 v[60:63], v253 offset0:44 offset1:46
	s_waitcnt lgkmcnt(7)
	v_mfma_f32_32x32x16_bf16 v[16:31], v[32:35], v[212:215], v[16:31]
	ds_read2_b64 v[32:35], v252 offset0:16 offset1:18
	s_waitcnt lgkmcnt(7)
	v_mfma_f32_32x32x16_bf16 v[0:15], v[36:39], v[212:215], v[0:15]
	ds_read2_b64 v[36:39], v253 offset0:48 offset1:50
	s_waitcnt lgkmcnt(7)
	v_mfma_f32_32x32x16_bf16 v[16:31], v[40:43], v[216:219], v[16:31]
	ds_read2_b64 v[40:43], v252 offset0:20 offset1:22
	s_waitcnt lgkmcnt(7)
	v_mfma_f32_32x32x16_bf16 v[0:15], v[44:47], v[216:219], v[0:15]
	ds_read2_b64 v[44:47], v253 offset0:52 offset1:54
	s_waitcnt lgkmcnt(7)
	v_mfma_f32_32x32x16_bf16 v[16:31], v[48:51], v[220:223], v[16:31]
	ds_read2_b64 v[48:51], v252 offset0:24 offset1:26
	s_waitcnt lgkmcnt(7)
	v_mfma_f32_32x32x16_bf16 v[0:15], v[52:55], v[220:223], v[0:15]
	ds_read2_b64 v[52:55], v253 offset0:56 offset1:58
	s_waitcnt lgkmcnt(7)
	v_mfma_f32_32x32x16_bf16 v[16:31], v[56:59], v[224:227], v[16:31]
	ds_read2_b64 v[56:59], v252 offset0:28 offset1:30
	s_waitcnt lgkmcnt(7)
	v_mfma_f32_32x32x16_bf16 v[0:15], v[60:63], v[224:227], v[0:15]
	ds_read2_b64 v[60:63], v253 offset0:60 offset1:62
	s_waitcnt lgkmcnt(7)
	v_mfma_f32_32x32x16_bf16 v[16:31], v[32:35], v[228:231], v[16:31]
	s_waitcnt lgkmcnt(6)
	v_mfma_f32_32x32x16_bf16 v[0:15], v[36:39], v[228:231], v[0:15]
	s_waitcnt lgkmcnt(5)
	v_mfma_f32_32x32x16_bf16 v[16:31], v[40:43], v[232:235], v[16:31]
	s_waitcnt lgkmcnt(4)
	v_mfma_f32_32x32x16_bf16 v[0:15], v[44:47], v[232:235], v[0:15]
	s_waitcnt lgkmcnt(0)
	s_barrier
	s_waitcnt lgkmcnt(3)
	v_mfma_f32_32x32x16_bf16 v[16:31], v[48:51], v[236:239], v[16:31]
	s_waitcnt lgkmcnt(2)
	v_mfma_f32_32x32x16_bf16 v[0:15], v[52:55], v[236:239], v[0:15]
	s_waitcnt lgkmcnt(1)
	v_mfma_f32_32x32x16_bf16 v[16:31], v[56:59], v[240:243], v[16:31]
	s_waitcnt lgkmcnt(0)
	v_mfma_f32_32x32x16_bf16 v[0:15], v[60:63], v[240:243], v[0:15]
	s_cmp_lg_u32 s0, 33
	s_cbranch_scc0 .LBB0_659
	v_mov_b32_e32 v172, v171
	s_mov_b32 s1, s0
	s_mov_b32 s98, s99
	s_add_i32 s99, s99, 0xaa00
	s_cmp_lt_u32 s99, 0x1fe00
	s_cselect_b32 s99, s99, 0
	s_branch .LBB0_663

.LBB0_2132:
	s_waitcnt lgkmcnt(0)
	s_barrier
	v_add3_u32 v252, s4, v142, v162
	v_add_u32_e32 v252, 0x6800, v252
	v_add_u32_e32 v253, 0x2000, v252
	v_exp_f32_e32 v80, v80
	v_exp_f32_e32 v81, v81
	v_exp_f32_e32 v82, v82
	v_exp_f32_e32 v83, v83
	v_exp_f32_e32 v84, v84
	v_exp_f32_e32 v85, v85
	v_exp_f32_e32 v86, v86
	v_exp_f32_e32 v87, v87
	v_lshl_add_u64 v[150:151], v[150:151], 0, s[16:17]
	v_lshl_add_u64 v[152:153], v[152:153], 0, s[16:17]
	v_lshl_add_u64 v[154:155], v[154:155], 0, s[14:15]
	v_lshl_add_u64 v[156:157], v[156:157], 0, s[14:15]
	v_lshl_add_u64 v[158:159], v[158:159], 0, s[14:15]
	v_exp_f32_e32 v88, v88
	v_exp_f32_e32 v89, v89
	v_exp_f32_e32 v90, v90
	v_exp_f32_e32 v91, v91
	v_exp_f32_e32 v92, v92
	v_exp_f32_e32 v93, v93
	v_exp_f32_e32 v94, v94
	v_exp_f32_e32 v95, v95
	v_add_f32_e32 v254, 0, v80
	v_add_f32_e32 v254, v81, v254
	v_add_f32_e32 v254, v82, v254
	v_add_f32_e32 v254, v83, v254
	v_add_f32_e32 v254, v84, v254
	v_add_f32_e32 v254, v85, v254
	v_add_f32_e32 v254, v86, v254
	v_add_f32_e32 v254, v87, v254
	v_cvt_pk_bf16_f32 v212, v80, v81
	v_cvt_pk_bf16_f32 v213, v82, v83
	v_cvt_pk_bf16_f32 v214, v84, v85
	v_cvt_pk_bf16_f32 v215, v86, v87
	v_exp_f32_e32 v64, v64
	v_exp_f32_e32 v65, v65
	v_exp_f32_e32 v66, v66
	v_exp_f32_e32 v67, v67
	v_exp_f32_e32 v68, v68
	v_exp_f32_e32 v69, v69
	v_exp_f32_e32 v70, v70
	v_exp_f32_e32 v71, v71
	v_add_f32_e32 v254, v88, v254
	v_add_f32_e32 v254, v89, v254
	v_add_f32_e32 v254, v90, v254
	v_add_f32_e32 v254, v91, v254
	v_add_f32_e32 v254, v92, v254
	v_add_f32_e32 v254, v93, v254
	v_add_f32_e32 v254, v94, v254
	v_add_f32_e32 v254, v95, v254
	v_cvt_pk_bf16_f32 v216, v88, v89
	v_cvt_pk_bf16_f32 v217, v90, v91
	v_cvt_pk_bf16_f32 v218, v92, v93
	v_cvt_pk_bf16_f32 v219, v94, v95
	v_exp_f32_e32 v72, v72
	v_exp_f32_e32 v73, v73
	v_exp_f32_e32 v74, v74
	v_exp_f32_e32 v75, v75
	v_exp_f32_e32 v76, v76
	v_exp_f32_e32 v77, v77
	v_exp_f32_e32 v78, v78
	v_exp_f32_e32 v79, v79
	v_add_f32_e32 v254, v64, v254
	v_add_f32_e32 v254, v65, v254
	v_add_f32_e32 v254, v66, v254
	v_add_f32_e32 v254, v67, v254
	v_add_f32_e32 v254, v68, v254
	v_add_f32_e32 v254, v69, v254
	v_add_f32_e32 v254, v70, v254
	v_add_f32_e32 v254, v71, v254
	v_cvt_pk_bf16_f32 v220, v64, v65
	v_cvt_pk_bf16_f32 v221, v66, v67
	v_cvt_pk_bf16_f32 v222, v68, v69
	v_cvt_pk_bf16_f32 v223, v70, v71
	v_exp_f32_e32 v48, v48
	v_exp_f32_e32 v49, v49
	v_exp_f32_e32 v50, v50
	v_exp_f32_e32 v51, v51
	v_exp_f32_e32 v52, v52
	v_exp_f32_e32 v53, v53
	v_exp_f32_e32 v54, v54
	v_exp_f32_e32 v55, v55
	v_add_f32_e32 v254, v72, v254
	v_add_f32_e32 v254, v73, v254
	v_add_f32_e32 v254, v74, v254
	v_add_f32_e32 v254, v75, v254
	v_add_f32_e32 v254, v76, v254
	v_add_f32_e32 v254, v77, v254
	v_add_f32_e32 v254, v78, v254
	v_add_f32_e32 v254, v79, v254
	v_cvt_pk_bf16_f32 v224, v72, v73
	v_cvt_pk_bf16_f32 v225, v74, v75
	v_cvt_pk_bf16_f32 v226, v76, v77
	v_cvt_pk_bf16_f32 v227, v78, v79
	v_exp_f32_e32 v56, v56
	v_exp_f32_e32 v57, v57
	v_exp_f32_e32 v58, v58
	v_exp_f32_e32 v59, v59
	v_exp_f32_e32 v60, v60
	v_exp_f32_e32 v61, v61
	v_exp_f32_e32 v62, v62
	v_exp_f32_e32 v63, v63
	v_add_f32_e32 v254, v48, v254
	v_add_f32_e32 v254, v49, v254
	v_add_f32_e32 v254, v50, v254
	v_add_f32_e32 v254, v51, v254
	v_add_f32_e32 v254, v52, v254
	v_add_f32_e32 v254, v53, v254
	v_add_f32_e32 v254, v54, v254
	v_add_f32_e32 v254, v55, v254
	v_cvt_pk_bf16_f32 v228, v48, v49
	v_cvt_pk_bf16_f32 v229, v50, v51
	v_cvt_pk_bf16_f32 v230, v52, v53
	v_cvt_pk_bf16_f32 v231, v54, v55
	v_exp_f32_e32 v32, v32
	v_exp_f32_e32 v33, v33
	v_exp_f32_e32 v34, v34
	v_exp_f32_e32 v35, v35
	v_exp_f32_e32 v36, v36
	v_exp_f32_e32 v37, v37
	v_exp_f32_e32 v38, v38
	v_exp_f32_e32 v39, v39
	v_add_f32_e32 v254, v56, v254
	v_add_f32_e32 v254, v57, v254
	v_add_f32_e32 v254, v58, v254
	v_add_f32_e32 v254, v59, v254
	v_add_f32_e32 v254, v60, v254
	v_add_f32_e32 v254, v61, v254
	v_add_f32_e32 v254, v62, v254
	v_add_f32_e32 v254, v63, v254
	v_cvt_pk_bf16_f32 v232, v56, v57
	v_cvt_pk_bf16_f32 v233, v58, v59
	v_cvt_pk_bf16_f32 v234, v60, v61
	v_cvt_pk_bf16_f32 v235, v62, v63
	v_exp_f32_e32 v40, v40
	v_exp_f32_e32 v41, v41
	v_exp_f32_e32 v42, v42
	v_exp_f32_e32 v43, v43
	v_exp_f32_e32 v44, v44
	v_exp_f32_e32 v45, v45
	v_exp_f32_e32 v46, v46
	v_exp_f32_e32 v47, v47
	v_add_f32_e32 v254, v32, v254
	v_add_f32_e32 v254, v33, v254
	v_add_f32_e32 v254, v34, v254
	v_add_f32_e32 v254, v35, v254
	v_add_f32_e32 v254, v36, v254
	v_add_f32_e32 v254, v37, v254
	v_add_f32_e32 v254, v38, v254
	v_add_f32_e32 v254, v39, v254
	v_cvt_pk_bf16_f32 v236, v32, v33
	v_cvt_pk_bf16_f32 v237, v34, v35
	v_cvt_pk_bf16_f32 v238, v36, v37
	v_cvt_pk_bf16_f32 v239, v38, v39
	s_nop 0
	v_add_f32_e32 v254, v40, v254
	v_add_f32_e32 v254, v41, v254
	v_add_f32_e32 v254, v42, v254
	v_add_f32_e32 v254, v43, v254
	v_add_f32_e32 v254, v44, v254
	v_add_f32_e32 v254, v45, v254
	v_add_f32_e32 v254, v46, v254
	v_add_f32_e32 v254, v47, v254
	v_cvt_pk_bf16_f32 v240, v40, v41
	v_cvt_pk_bf16_f32 v241, v42, v43
	v_cvt_pk_bf16_f32 v242, v44, v45
	v_cvt_pk_bf16_f32 v243, v46, v47
	v_add_f32_e32 v149, v149, v254
	ds_read2_b64 v[32:35], v252 offset1:2
	ds_read2_b64 v[36:39], v253 offset0:32 offset1:34
	ds_read2_b64 v[40:43], v252 offset0:4 offset1:6
	ds_read2_b64 v[44:47], v253 offset0:36 offset1:38
	ds_read2_b64 v[48:51], v252 offset0:8 offset1:10
	ds_read2_b64 v[52:55], v253 offset0:40 offset1:42
	ds_read2_b64 v[56:59], v252 offset0:12 offset1:14
	ds_read2_b64 v[60:63], v253 offset0:44 offset1:46
	s_waitcnt lgkmcnt(7)
	v_mfma_f32_32x32x16_bf16 v[16:31], v[32:35], v[212:215], v[16:31]
	ds_read2_b64 v[32:35], v252 offset0:16 offset1:18
	s_waitcnt lgkmcnt(7)
	v_mfma_f32_32x32x16_bf16 v[0:15], v[36:39], v[212:215], v[0:15]
	ds_read2_b64 v[36:39], v253 offset0:48 offset1:50
	s_waitcnt lgkmcnt(7)
	v_mfma_f32_32x32x16_bf16 v[16:31], v[40:43], v[216:219], v[16:31]
	ds_read2_b64 v[40:43], v252 offset0:20 offset1:22
	s_waitcnt lgkmcnt(7)
	v_mfma_f32_32x32x16_bf16 v[0:15], v[44:47], v[216:219], v[0:15]
	ds_read2_b64 v[44:47], v253 offset0:52 offset1:54
	s_waitcnt lgkmcnt(7)
	v_mfma_f32_32x32x16_bf16 v[16:31], v[48:51], v[220:223], v[16:31]
	ds_read2_b64 v[48:51], v252 offset0:24 offset1:26
	s_waitcnt lgkmcnt(7)
	v_mfma_f32_32x32x16_bf16 v[0:15], v[52:55], v[220:223], v[0:15]
	ds_read2_b64 v[52:55], v253 offset0:56 offset1:58
	s_waitcnt lgkmcnt(7)
	v_mfma_f32_32x32x16_bf16 v[16:31], v[56:59], v[224:227], v[16:31]
	ds_read2_b64 v[56:59], v252 offset0:28 offset1:30
	s_waitcnt lgkmcnt(7)
	v_mfma_f32_32x32x16_bf16 v[0:15], v[60:63], v[224:227], v[0:15]
	ds_read2_b64 v[60:63], v253 offset0:60 offset1:62
	s_waitcnt lgkmcnt(7)
	v_mfma_f32_32x32x16_bf16 v[16:31], v[32:35], v[228:231], v[16:31]
	s_waitcnt lgkmcnt(6)
	v_mfma_f32_32x32x16_bf16 v[0:15], v[36:39], v[228:231], v[0:15]
	s_waitcnt lgkmcnt(5)
	v_mfma_f32_32x32x16_bf16 v[16:31], v[40:43], v[232:235], v[16:31]
	s_waitcnt lgkmcnt(4)
	v_mfma_f32_32x32x16_bf16 v[0:15], v[44:47], v[232:235], v[0:15]
	s_waitcnt lgkmcnt(0)
	s_barrier
	s_waitcnt lgkmcnt(3)
	v_mfma_f32_32x32x16_bf16 v[16:31], v[48:51], v[236:239], v[16:31]
	s_waitcnt lgkmcnt(2)
	v_mfma_f32_32x32x16_bf16 v[0:15], v[52:55], v[236:239], v[0:15]
	s_waitcnt lgkmcnt(1)
	v_mfma_f32_32x32x16_bf16 v[16:31], v[56:59], v[240:243], v[16:31]
	s_waitcnt lgkmcnt(0)
	v_mfma_f32_32x32x16_bf16 v[0:15], v[60:63], v[240:243], v[0:15]
	s_cmp_lg_u32 s2, 33
	s_cbranch_scc0 .LBB0_2123
	v_mov_b32_e32 v172, v171
	s_mov_b32 s4, s2
	s_mov_b32 s98, s99
	s_add_i32 s99, s99, 0xaa00
	s_cmp_lt_u32 s99, 0x1fe00
	s_cselect_b32 s99, s99, 0
	s_branch .LBB0_2127
